# fin-ffn tail rows: the 4+4 serial gpost/gnext vector loads (each followed by vmcnt(0), which also waited for the previous store) issued together up front into spare registers
# baseline (speedup 1.0000x reference)
.LBB0_126:
	s_ashr_i32 s59, s58, 31
	s_lshl_b64 s[16:17], s[58:59], 12
	v_lshl_add_u64 v[0:1], v[70:71], 0, s[16:17]
	v_add_co_u32_e32 v4, vcc, 0x300000, v0
	global_load_dwordx4 v[74:77], v[0:1], off
	s_nop 0
	v_addc_co_u32_e32 v5, vcc, 0, v1, vcc
	v_add_co_u32_e32 v10, vcc, 0x600000, v0
	global_load_dwordx4 v[78:81], v[4:5], off
	s_nop 0
	v_addc_co_u32_e32 v11, vcc, 0, v1, vcc
	s_waitcnt vmcnt(4)
	v_add_co_u32_e32 v14, vcc, 0x900000, v0
	global_load_dwordx4 v[82:85], v[10:11], off
	s_nop 0
	v_addc_co_u32_e32 v15, vcc, 0, v1, vcc
	s_waitcnt vmcnt(4)
	v_add_co_u32_e32 v18, vcc, 0xc00000, v0
	global_load_dwordx4 v[86:89], v[14:15], off
	s_nop 0
	v_addc_co_u32_e32 v19, vcc, 0, v1, vcc
	v_add_co_u32_e32 v22, vcc, 0xf00000, v0
	global_load_dwordx4 v[90:93], v[18:19], off
	s_nop 0
	v_addc_co_u32_e32 v23, vcc, 0, v1, vcc
	s_waitcnt vmcnt(5)
	v_add_co_u32_e32 v26, vcc, 0x1200000, v0
	global_load_dwordx4 v[100:103], v[22:23], off
	s_nop 0
	v_addc_co_u32_e32 v27, vcc, 0, v1, vcc
	v_add_co_u32_e32 v30, vcc, 0x1500000, v0
	global_load_dwordx4 v[104:107], v[26:27], off
	s_nop 0
	v_addc_co_u32_e32 v31, vcc, 0, v1, vcc
	v_add_co_u32_e32 v34, vcc, 0x1800000, v0
	global_load_dwordx4 v[108:111], v[30:31], off
	s_nop 0
	v_addc_co_u32_e32 v35, vcc, 0, v1, vcc
	v_add_co_u32_e32 v38, vcc, 0x1b00000, v0
	s_waitcnt lgkmcnt(0)
	global_load_dwordx4 v[112:115], v[34:35], off
	v_addc_co_u32_e32 v39, vcc, 0, v1, vcc
	v_add_co_u32_e32 v42, vcc, 0x1e00000, v0
	global_load_dwordx4 v[116:119], v[38:39], off
	s_nop 0
	v_addc_co_u32_e32 v43, vcc, 0, v1, vcc
	v_add_co_u32_e32 v46, vcc, 0x2100000, v0
	global_load_dwordx4 v[120:123], v[42:43], off
	s_nop 0
	v_addc_co_u32_e32 v47, vcc, 0, v1, vcc
	v_add_co_u32_e32 v50, vcc, 0x2400000, v0
	global_load_dwordx4 v[124:127], v[46:47], off
	s_nop 0
	v_addc_co_u32_e32 v51, vcc, 0, v1, vcc
	v_add_co_u32_e32 v54, vcc, 0x2700000, v0
	global_load_dwordx4 v[128:131], v[50:51], off
	s_nop 0
	v_addc_co_u32_e32 v55, vcc, 0, v1, vcc
	v_add_co_u32_e32 v58, vcc, 0x2a00000, v0
	global_load_dwordx4 v[132:135], v[54:55], off
	s_nop 0
	v_addc_co_u32_e32 v59, vcc, 0, v1, vcc
	v_add_co_u32_e32 v62, vcc, 0x2d00000, v0
	global_load_dwordx4 v[136:139], v[58:59], off
	s_nop 0
	v_addc_co_u32_e32 v63, vcc, 0, v1, vcc
	global_load_dwordx4 v[140:143], v[62:63], off
	s_lshl_b64 s[64:65], s[64:65], 12
	s_add_u32 s64, s44, s64
	s_addc_u32 s65, s45, s65
	s_cmp_lt_i32 s14, 0x10200
	s_mov_b64 s[66:67], -1
	s_waitcnt vmcnt(14)
	v_pk_add_f32 v[2:3], v[76:77], v[80:81]
	v_pk_add_f32 v[6:7], v[74:75], v[78:79]
	s_waitcnt vmcnt(13)
	v_pk_add_f32 v[2:3], v[84:85], v[2:3]
	v_pk_add_f32 v[6:7], v[82:83], v[6:7]
	s_waitcnt vmcnt(12)
	v_pk_add_f32 v[2:3], v[88:89], v[2:3]
	v_pk_add_f32 v[6:7], v[86:87], v[6:7]
	s_waitcnt vmcnt(11)
	v_pk_add_f32 v[2:3], v[92:93], v[2:3]
	v_pk_add_f32 v[6:7], v[90:91], v[6:7]
	s_waitcnt vmcnt(10)
	v_pk_add_f32 v[2:3], v[102:103], v[2:3]
	v_pk_add_f32 v[6:7], v[100:101], v[6:7]
	s_waitcnt vmcnt(9)
	v_pk_add_f32 v[2:3], v[106:107], v[2:3]
	v_pk_add_f32 v[6:7], v[104:105], v[6:7]
	s_waitcnt vmcnt(8)
	v_pk_add_f32 v[2:3], v[110:111], v[2:3]
	v_pk_add_f32 v[6:7], v[108:109], v[6:7]
	s_waitcnt vmcnt(7)
	v_pk_add_f32 v[2:3], v[114:115], v[2:3]
	v_pk_add_f32 v[6:7], v[112:113], v[6:7]
	s_waitcnt vmcnt(6)
	v_pk_add_f32 v[2:3], v[118:119], v[2:3]
	v_pk_add_f32 v[6:7], v[116:117], v[6:7]
	s_waitcnt vmcnt(5)
	v_pk_add_f32 v[2:3], v[122:123], v[2:3]
	v_pk_add_f32 v[6:7], v[120:121], v[6:7]
	s_waitcnt vmcnt(4)
	v_pk_add_f32 v[2:3], v[126:127], v[2:3]
	v_pk_add_f32 v[6:7], v[124:125], v[6:7]
	s_waitcnt vmcnt(3)
	v_pk_add_f32 v[2:3], v[130:131], v[2:3]
	v_pk_add_f32 v[6:7], v[128:129], v[6:7]
	s_waitcnt vmcnt(2)
	v_pk_add_f32 v[2:3], v[134:135], v[2:3]
	v_pk_add_f32 v[6:7], v[132:133], v[6:7]
	s_waitcnt vmcnt(1)
	v_pk_add_f32 v[2:3], v[138:139], v[2:3]
	v_pk_add_f32 v[6:7], v[136:137], v[6:7]
	s_waitcnt vmcnt(0)
	v_pk_add_f32 v[76:77], v[142:143], v[2:3]
	global_load_dwordx2 v[2:3], v[72:73], off
	v_pk_add_f32 v[80:81], v[140:141], v[6:7]
	global_load_dwordx4 v[82:85], v[0:1], off offset:1024
	global_load_dwordx4 v[86:89], v[4:5], off offset:1024
	global_load_dwordx4 v[90:93], v[10:11], off offset:1024
	global_load_dwordx4 v[100:103], v[14:15], off offset:1024
	global_load_dwordx4 v[104:107], v[18:19], off offset:1024
	global_load_dwordx4 v[108:111], v[22:23], off offset:1024
	global_load_dwordx4 v[112:115], v[26:27], off offset:1024
	global_load_dwordx4 v[116:119], v[30:31], off offset:1024
	global_load_dwordx4 v[120:123], v[34:35], off offset:1024
	global_load_dwordx4 v[124:127], v[38:39], off offset:1024
	global_load_dwordx4 v[128:131], v[42:43], off offset:1024
	global_load_dwordx4 v[132:135], v[46:47], off offset:1024
	global_load_dwordx4 v[136:139], v[50:51], off offset:1024
	global_load_dwordx4 v[140:143], v[54:55], off offset:1024
	global_load_dwordx4 v[150:153], v[58:59], off offset:1024
	global_load_dwordx4 v[154:157], v[62:63], off offset:1024
	v_mul_f32_e32 v12, v81, v81
	v_fmac_f32_e32 v12, v80, v80
	v_fmac_f32_e32 v12, v76, v76
	v_fmac_f32_e32 v12, v77, v77
	s_waitcnt vmcnt(14)
	v_pk_add_f32 v[6:7], v[82:83], v[86:87]
	s_waitcnt vmcnt(13)
	v_pk_add_f32 v[6:7], v[90:91], v[6:7]
	global_load_dwordx2 v[86:87], v[72:73], off offset:512
	s_waitcnt vmcnt(13)
	v_pk_add_f32 v[6:7], v[100:101], v[6:7]
	v_lshlrev_b32_e32 v74, 16, v2
	v_and_b32_e32 v75, 0xffff0000, v2
	v_lshlrev_b32_e32 v78, 16, v3
	v_and_b32_e32 v79, 0xffff0000, v3
	v_pk_add_f32 v[2:3], v[84:85], v[88:89]
	s_waitcnt vmcnt(12)
	v_pk_add_f32 v[6:7], v[104:105], v[6:7]
	v_pk_add_f32 v[2:3], v[92:93], v[2:3]
	s_waitcnt vmcnt(11)
	v_pk_add_f32 v[6:7], v[108:109], v[6:7]
	v_pk_add_f32 v[2:3], v[102:103], v[2:3]
	s_waitcnt vmcnt(10)
	v_pk_add_f32 v[6:7], v[112:113], v[6:7]
	v_pk_add_f32 v[2:3], v[106:107], v[2:3]
	s_waitcnt vmcnt(9)
	v_pk_add_f32 v[6:7], v[116:117], v[6:7]
	v_pk_add_f32 v[2:3], v[110:111], v[2:3]
	s_waitcnt vmcnt(8)
	v_pk_add_f32 v[6:7], v[120:121], v[6:7]
	v_pk_add_f32 v[2:3], v[114:115], v[2:3]
	s_waitcnt vmcnt(7)
	v_pk_add_f32 v[6:7], v[124:125], v[6:7]
	v_pk_add_f32 v[2:3], v[118:119], v[2:3]
	s_waitcnt vmcnt(6)
	v_pk_add_f32 v[6:7], v[128:129], v[6:7]
	v_pk_add_f32 v[2:3], v[122:123], v[2:3]
	s_waitcnt vmcnt(5)
	v_pk_add_f32 v[6:7], v[132:133], v[6:7]
	v_pk_add_f32 v[2:3], v[126:127], v[2:3]
	s_waitcnt vmcnt(4)
	v_pk_add_f32 v[6:7], v[136:137], v[6:7]
	v_pk_add_f32 v[2:3], v[130:131], v[2:3]
	s_waitcnt vmcnt(3)
	v_pk_add_f32 v[6:7], v[140:141], v[6:7]
	v_pk_add_f32 v[2:3], v[134:135], v[2:3]
	s_waitcnt vmcnt(2)
	v_pk_add_f32 v[6:7], v[150:151], v[6:7]
	v_pk_add_f32 v[2:3], v[138:139], v[2:3]
	s_waitcnt vmcnt(1)
	v_pk_add_f32 v[84:85], v[154:155], v[6:7]
	v_pk_add_f32 v[2:3], v[142:143], v[2:3]
	s_nop 0
	v_pk_add_f32 v[2:3], v[152:153], v[2:3]
	s_nop 0
	v_pk_add_f32 v[82:83], v[156:157], v[2:3]
	global_load_dwordx4 v[88:91], v[0:1], off offset:2048
	global_load_dwordx4 v[100:103], v[4:5], off offset:2048
	global_load_dwordx4 v[104:107], v[10:11], off offset:2048
	global_load_dwordx4 v[108:111], v[14:15], off offset:2048
	global_load_dwordx4 v[112:115], v[18:19], off offset:2048
	global_load_dwordx4 v[116:119], v[22:23], off offset:2048
	global_load_dwordx4 v[120:123], v[26:27], off offset:2048
	global_load_dwordx4 v[124:127], v[30:31], off offset:2048
	global_load_dwordx4 v[128:131], v[34:35], off offset:2048
	global_load_dwordx4 v[132:135], v[38:39], off offset:2048
	global_load_dwordx4 v[136:139], v[42:43], off offset:2048
	global_load_dwordx4 v[140:143], v[46:47], off offset:2048
	global_load_dwordx4 v[150:153], v[50:51], off offset:2048
	global_load_dwordx4 v[154:157], v[54:55], off offset:2048
	global_load_dwordx4 v[158:161], v[58:59], off offset:2048
	global_load_dwordx4 v[162:165], v[62:63], off offset:2048
	v_mul_f32_e32 v2, v85, v85
	v_fmac_f32_e32 v2, v84, v84
	v_fmac_f32_e32 v2, v82, v82
	v_fmac_f32_e32 v2, v83, v83
	v_add_f32_e32 v99, v12, v2
	s_waitcnt vmcnt(14)
	v_pk_add_f32 v[2:3], v[90:91], v[102:103]
	v_pk_add_f32 v[6:7], v[88:89], v[100:101]
	s_waitcnt vmcnt(13)
	v_pk_add_f32 v[2:3], v[106:107], v[2:3]
	v_pk_add_f32 v[6:7], v[104:105], v[6:7]
	s_waitcnt vmcnt(12)
	v_pk_add_f32 v[2:3], v[110:111], v[2:3]
	v_pk_add_f32 v[6:7], v[108:109], v[6:7]
	s_waitcnt vmcnt(11)
	v_pk_add_f32 v[2:3], v[114:115], v[2:3]
	v_pk_add_f32 v[6:7], v[112:113], v[6:7]
	s_waitcnt vmcnt(10)
	v_pk_add_f32 v[2:3], v[118:119], v[2:3]
	v_pk_add_f32 v[6:7], v[116:117], v[6:7]
	s_waitcnt vmcnt(9)
	v_pk_add_f32 v[2:3], v[122:123], v[2:3]
	v_pk_add_f32 v[6:7], v[120:121], v[6:7]
	s_waitcnt vmcnt(8)
	v_pk_add_f32 v[2:3], v[126:127], v[2:3]
	v_pk_add_f32 v[6:7], v[124:125], v[6:7]
	s_waitcnt vmcnt(7)
	v_pk_add_f32 v[2:3], v[130:131], v[2:3]
	v_pk_add_f32 v[6:7], v[128:129], v[6:7]
	s_waitcnt vmcnt(6)
	v_pk_add_f32 v[2:3], v[134:135], v[2:3]
	v_pk_add_f32 v[6:7], v[132:133], v[6:7]
	s_waitcnt vmcnt(5)
	v_pk_add_f32 v[2:3], v[138:139], v[2:3]
	v_pk_add_f32 v[6:7], v[136:137], v[6:7]
	s_waitcnt vmcnt(4)
	v_pk_add_f32 v[2:3], v[142:143], v[2:3]
	v_pk_add_f32 v[6:7], v[140:141], v[6:7]
	s_waitcnt vmcnt(3)
	v_pk_add_f32 v[2:3], v[152:153], v[2:3]
	v_pk_add_f32 v[6:7], v[150:151], v[6:7]
	s_waitcnt vmcnt(2)
	v_pk_add_f32 v[2:3], v[156:157], v[2:3]
	v_pk_add_f32 v[6:7], v[154:155], v[6:7]
	s_waitcnt vmcnt(1)
	v_pk_add_f32 v[2:3], v[160:161], v[2:3]
	v_pk_add_f32 v[6:7], v[158:159], v[6:7]
	s_waitcnt vmcnt(0)
	v_pk_add_f32 v[88:89], v[164:165], v[2:3]
	v_pk_add_f32 v[90:91], v[162:163], v[6:7]
	global_load_dwordx2 v[92:93], v[72:73], off offset:1024
	s_nop 0
	global_load_dwordx4 v[0:3], v[0:1], off offset:3072
	s_nop 0
	global_load_dwordx4 v[4:7], v[4:5], off offset:3072
	s_nop 0
	global_load_dwordx4 v[10:13], v[10:11], off offset:3072
	s_nop 0
	global_load_dwordx4 v[14:17], v[14:15], off offset:3072
	s_nop 0
	global_load_dwordx4 v[18:21], v[18:19], off offset:3072
	s_nop 0
	global_load_dwordx4 v[22:25], v[22:23], off offset:3072
	s_nop 0
	global_load_dwordx4 v[26:29], v[26:27], off offset:3072
	s_nop 0
	global_load_dwordx4 v[30:33], v[30:31], off offset:3072
	s_nop 0
	global_load_dwordx4 v[34:37], v[34:35], off offset:3072
	s_nop 0
	global_load_dwordx4 v[38:41], v[38:39], off offset:3072
	s_nop 0
	global_load_dwordx4 v[42:45], v[42:43], off offset:3072
	s_nop 0
	global_load_dwordx4 v[46:49], v[46:47], off offset:3072
	s_nop 0
	global_load_dwordx4 v[50:53], v[50:51], off offset:3072
	s_nop 0
	global_load_dwordx4 v[54:57], v[54:55], off offset:3072
	s_nop 0
	global_load_dwordx4 v[58:61], v[58:59], off offset:3072
	s_nop 0
	global_load_dwordx4 v[62:65], v[62:63], off offset:3072
	s_waitcnt vmcnt(14)
	v_pk_add_f32 v[2:3], v[2:3], v[6:7]
	v_pk_add_f32 v[0:1], v[0:1], v[4:5]
	s_waitcnt vmcnt(13)
	v_pk_add_f32 v[2:3], v[12:13], v[2:3]
	v_pk_add_f32 v[0:1], v[10:11], v[0:1]
	s_waitcnt vmcnt(12)
	v_pk_add_f32 v[2:3], v[16:17], v[2:3]
	v_pk_add_f32 v[0:1], v[14:15], v[0:1]
	s_waitcnt vmcnt(11)
	v_pk_add_f32 v[2:3], v[20:21], v[2:3]
	v_pk_add_f32 v[0:1], v[18:19], v[0:1]
	s_waitcnt vmcnt(10)
	v_pk_add_f32 v[2:3], v[24:25], v[2:3]
	v_pk_add_f32 v[0:1], v[22:23], v[0:1]
	s_waitcnt vmcnt(9)
	v_pk_add_f32 v[2:3], v[28:29], v[2:3]
	v_pk_add_f32 v[0:1], v[26:27], v[0:1]
	s_waitcnt vmcnt(8)
	v_pk_add_f32 v[2:3], v[32:33], v[2:3]
	v_pk_add_f32 v[0:1], v[30:31], v[0:1]
	s_waitcnt vmcnt(7)
	v_pk_add_f32 v[2:3], v[36:37], v[2:3]
	v_pk_add_f32 v[0:1], v[34:35], v[0:1]
	s_waitcnt vmcnt(6)
	v_pk_add_f32 v[2:3], v[40:41], v[2:3]
	v_pk_add_f32 v[0:1], v[38:39], v[0:1]
	s_waitcnt vmcnt(5)
	v_pk_add_f32 v[2:3], v[44:45], v[2:3]
	v_pk_add_f32 v[0:1], v[42:43], v[0:1]
	s_waitcnt vmcnt(4)
	v_pk_add_f32 v[2:3], v[48:49], v[2:3]
	v_pk_add_f32 v[0:1], v[46:47], v[0:1]
	s_waitcnt vmcnt(3)
	v_pk_add_f32 v[2:3], v[52:53], v[2:3]
	v_pk_add_f32 v[0:1], v[50:51], v[0:1]
	s_waitcnt vmcnt(2)
	v_pk_add_f32 v[2:3], v[56:57], v[2:3]
	v_pk_add_f32 v[0:1], v[54:55], v[0:1]
	s_waitcnt vmcnt(1)
	v_pk_add_f32 v[2:3], v[60:61], v[2:3]
	v_pk_add_f32 v[4:5], v[58:59], v[0:1]
	s_waitcnt vmcnt(0)
	v_pk_add_f32 v[0:1], v[64:65], v[2:3]
	v_pk_add_f32 v[2:3], v[62:63], v[4:5]
	v_mov_b32_e32 v6, v91
	v_mov_b32_e32 v7, v3
	v_mov_b32_e32 v4, v90
	v_mov_b32_e32 v5, v2
	v_pk_mul_f32 v[6:7], v[6:7], v[6:7]
	global_load_dwordx2 v[18:19], v[72:73], off offset:1536
	v_pk_fma_f32 v[4:5], v[4:5], v[4:5], v[6:7]
	v_mov_b32_e32 v6, v88
	v_mov_b32_e32 v7, v0
	v_pk_fma_f32 v[4:5], v[6:7], v[6:7], v[4:5]
	v_mov_b32_e32 v6, v89
	v_mov_b32_e32 v7, v1
	v_pk_fma_f32 v[4:5], v[6:7], v[6:7], v[4:5]
	s_nop 0
	v_add_f32_e32 v4, v99, v4
	v_add_f32_e32 v4, v4, v5
	ds_bpermute_b32 v5, v9, v4
	s_waitcnt lgkmcnt(0)
	v_add_f32_e32 v4, v4, v5
	ds_bpermute_b32 v5, v94, v4
	s_waitcnt lgkmcnt(0)
	v_add_f32_e32 v4, v4, v5
	ds_bpermute_b32 v5, v95, v4
	s_waitcnt lgkmcnt(0)
	v_add_f32_e32 v4, v4, v5
	ds_bpermute_b32 v5, v96, v4
	s_waitcnt lgkmcnt(0)
	v_add_f32_e32 v4, v4, v5
	ds_bpermute_b32 v5, v97, v4
	s_waitcnt lgkmcnt(0)
	v_add_f32_e32 v4, v4, v5
	ds_bpermute_b32 v5, v98, v4
	s_waitcnt lgkmcnt(0)
	v_add_f32_e32 v4, v4, v5
	v_fmamk_f32 v4, v4, 0x3a800000, v198
	v_cmp_gt_f32_e32 vcc, s31, v4
	v_mul_f32_e32 v5, 0x4f800000, v4
	s_nop 0
	v_cndmask_b32_e32 v4, v4, v5, vcc
	v_sqrt_f32_e32 v5, v4
	s_nop 0
	v_add_u32_e32 v6, -1, v5
	v_fma_f32 v7, -v6, v5, v4
	v_cmp_ge_f32_e64 s[44:45], 0, v7
	v_add_u32_e32 v7, 1, v5
	s_nop 0
	v_cndmask_b32_e64 v6, v5, v6, s[44:45]
	v_fma_f32 v5, -v7, v5, v4
	v_cmp_lt_f32_e64 s[44:45], 0, v5
	s_nop 1
	v_cndmask_b32_e64 v5, v6, v7, s[44:45]
	v_mul_f32_e32 v6, 0x37800000, v5
	v_cndmask_b32_e32 v5, v5, v6, vcc
	v_cmp_class_f32_e32 vcc, v4, v199
	s_cselect_b64 s[44:45], -1, 0
	s_nop 0
	v_cndmask_b32_e32 v4, v5, v4, vcc
	v_div_scale_f32 v5, s[16:17], v4, v4, 1.0
	v_rcp_f32_e32 v6, v5
	s_nop 0
	v_fma_f32 v7, -v5, v6, 1.0
	v_fmac_f32_e32 v6, v7, v6
	v_div_scale_f32 v7, vcc, 1.0, v4, 1.0
	v_mul_f32_e32 v10, v7, v6
	v_fma_f32 v11, -v5, v10, v7
	v_fmac_f32_e32 v10, v11, v6
	v_fma_f32 v5, -v5, v10, v7
	v_div_fmas_f32 v5, v5, v6, v10
	v_div_fixup_f32 v20, v5, v4, 1.0
	global_load_dwordx4 v[4:7], v[66:67], off
	global_load_dwordx4 v[170:173], v[66:67], off offset:1024
	global_load_dwordx4 v[174:177], v[66:67], off offset:2048
	global_load_dwordx4 v[178:181], v[66:67], off offset:3072
	v_pk_mul_f32 v[10:11], v[80:81], v[20:21] op_sel_hi:[1,0]
	v_pk_mul_f32 v[12:13], v[76:77], v[20:21] op_sel_hi:[1,0]
	s_and_b64 vcc, exec, s[46:47]
	s_waitcnt vmcnt(0)
	v_pk_fma_f32 v[12:13], v[6:7], v[12:13], v[78:79]
	v_pk_fma_f32 v[10:11], v[4:5], v[10:11], v[74:75]
	s_cbranch_vccz .LBB0_128
	v_cvt_pk_bf16_f32 v4, v10, v11
	v_cvt_pk_bf16_f32 v5, v12, v13
	global_store_dwordx2 v[72:73], v[4:5], off
	s_mov_b64 s[66:67], 0

.LBB0_131:
	s_nop 1
	v_mov_b32_e32 v4, v170
	v_mov_b32_e32 v5, v171
	v_mov_b32_e32 v6, v172
	v_mov_b32_e32 v7, v173
	v_mov_b32_e32 v21, v20
	v_mov_b32_e32 v24, v20
	v_mov_b32_e32 v25, v20
	v_lshlrev_b32_e32 v14, 16, v86
	v_and_b32_e32 v15, 0xffff0000, v86
	v_lshlrev_b32_e32 v16, 16, v87
	v_and_b32_e32 v17, 0xffff0000, v87
	v_pk_mul_f32 v[24:25], v[82:83], v[24:25]
	v_pk_mul_f32 v[26:27], v[84:85], v[20:21]
	s_and_b64 vcc, exec, s[42:43]
	s_mov_b64 s[64:65], -1
	v_pk_fma_f32 v[16:17], v[24:25], v[6:7], v[16:17]
	v_pk_fma_f32 v[14:15], v[26:27], v[4:5], v[14:15]
	s_cbranch_vccnz .LBB0_133
	v_cvt_pk_bf16_f32 v4, v14, v15
	v_cvt_pk_bf16_f32 v5, v16, v17
	s_mov_b64 s[64:65], 0
	global_store_dwordx2 v[72:73], v[4:5], off offset:512

.LBB0_136:
	s_nop 1
	v_mov_b32_e32 v4, v174
	v_mov_b32_e32 v5, v175
	v_mov_b32_e32 v6, v176
	v_mov_b32_e32 v7, v177
	v_mov_b32_e32 v28, v20
	v_mov_b32_e32 v29, v20
	v_lshlrev_b32_e32 v24, 16, v92
	v_and_b32_e32 v25, 0xffff0000, v92
	v_lshlrev_b32_e32 v26, 16, v93
	v_and_b32_e32 v27, 0xffff0000, v93
	v_pk_mul_f32 v[30:31], v[90:91], v[20:21]
	v_pk_mul_f32 v[28:29], v[88:89], v[28:29]
	s_and_b64 vcc, exec, s[42:43]
	s_mov_b64 s[64:65], -1
	v_pk_fma_f32 v[6:7], v[28:29], v[6:7], v[26:27]
	v_pk_fma_f32 v[4:5], v[30:31], v[4:5], v[24:25]
	s_cbranch_vccnz .LBB0_138
	v_cvt_pk_bf16_f32 v24, v4, v5
	v_cvt_pk_bf16_f32 v25, v6, v7
	s_mov_b64 s[64:65], 0
	global_store_dwordx2 v[72:73], v[24:25], off offset:1024

.LBB0_141:
	s_nop 1
	v_mov_b32_e32 v24, v178
	v_mov_b32_e32 v25, v179
	v_mov_b32_e32 v26, v180
	v_mov_b32_e32 v27, v181
	v_mov_b32_e32 v30, v20
	v_mov_b32_e32 v31, v20
	v_lshlrev_b32_e32 v28, 16, v18
	v_and_b32_e32 v29, 0xffff0000, v18
	v_lshlrev_b32_e32 v18, 16, v19
	v_and_b32_e32 v19, 0xffff0000, v19
	v_pk_mul_f32 v[20:21], v[2:3], v[20:21]
	v_pk_mul_f32 v[0:1], v[0:1], v[30:31]
	s_and_b64 vcc, exec, s[42:43]
	s_mov_b64 s[64:65], -1
	v_pk_fma_f32 v[2:3], v[0:1], v[26:27], v[18:19]
	v_pk_fma_f32 v[0:1], v[20:21], v[24:25], v[28:29]
	s_cbranch_vccnz .LBB0_143
	v_cvt_pk_bf16_f32 v18, v0, v1
	v_cvt_pk_bf16_f32 v19, v2, v3
	s_mov_b64 s[64:65], 0
	global_store_dwordx2 v[72:73], v[18:19], off offset:1536

.LBB0_146:
	s_and_b64 vcc, exec, s[42:43]
	s_cbranch_vccnz .LBB0_120
	v_mul_f32_e32 v18, v11, v11
	v_mul_f32_e32 v19, v15, v15
	v_fmac_f32_e32 v18, v10, v10
	v_fmac_f32_e32 v19, v14, v14
	v_fmac_f32_e32 v18, v12, v12
	v_fmac_f32_e32 v19, v16, v16
	v_fmac_f32_e32 v18, v13, v13
	v_fmac_f32_e32 v19, v17, v17
	v_add_f32_e32 v18, v18, v19
	v_mul_f32_e32 v19, v5, v5
	v_fmac_f32_e32 v19, v4, v4
	v_fmac_f32_e32 v19, v6, v6
	v_fmac_f32_e32 v19, v7, v7
	v_add_f32_e32 v18, v18, v19
	v_mul_f32_e32 v19, v1, v1
	v_fmac_f32_e32 v19, v0, v0
	v_fmac_f32_e32 v19, v2, v2
	v_fmac_f32_e32 v19, v3, v3
	v_add_f32_e32 v18, v18, v19
	ds_bpermute_b32 v19, v9, v18
	v_mov_b32_e32 v25, v12
	v_mov_b32_e32 v12, v11
	v_mov_b32_e32 v24, v10
	s_mov_b32 s3, 0xaf601000
	s_waitcnt lgkmcnt(0)
	v_add_f32_e32 v18, v18, v19
	ds_bpermute_b32 v19, v94, v18
	s_waitcnt lgkmcnt(0)
	v_add_f32_e32 v18, v18, v19
	ds_bpermute_b32 v19, v95, v18
	s_waitcnt lgkmcnt(0)
	v_add_f32_e32 v18, v18, v19
	ds_bpermute_b32 v19, v96, v18
	s_waitcnt lgkmcnt(0)
	v_add_f32_e32 v18, v18, v19
	ds_bpermute_b32 v19, v97, v18
	s_waitcnt lgkmcnt(0)
	v_add_f32_e32 v18, v18, v19
	ds_bpermute_b32 v19, v98, v18
	s_waitcnt lgkmcnt(0)
	v_add_f32_e32 v18, v18, v19
	v_fmamk_f32 v18, v18, 0x3a800000, v198
	v_cmp_gt_f32_e32 vcc, s31, v18
	v_mul_f32_e32 v19, 0x4f800000, v18
	s_nop 0
	v_cndmask_b32_e32 v18, v18, v19, vcc
	v_sqrt_f32_e32 v19, v18
	s_nop 0
	v_add_u32_e32 v20, -1, v19
	v_fma_f32 v21, -v20, v19, v18
	v_cmp_ge_f32_e64 s[44:45], 0, v21
	v_add_u32_e32 v21, 1, v19
	s_nop 0
	v_cndmask_b32_e64 v20, v19, v20, s[44:45]
	v_fma_f32 v19, -v21, v19, v18
	v_cmp_lt_f32_e64 s[44:45], 0, v19
	s_nop 1
	v_cndmask_b32_e64 v19, v20, v21, s[44:45]
	v_mul_f32_e32 v20, 0x37800000, v19
	v_cndmask_b32_e32 v19, v19, v20, vcc
	v_cmp_class_f32_e32 vcc, v18, v199
	s_nop 1
	v_cndmask_b32_e32 v18, v19, v18, vcc
	v_div_scale_f32 v19, s[14:15], v18, v18, 1.0
	v_rcp_f32_e32 v20, v19
	s_nop 0
	v_fma_f32 v21, -v19, v20, 1.0
	v_fmac_f32_e32 v20, v21, v20
	v_div_scale_f32 v21, vcc, 1.0, v18, 1.0
	v_mul_f32_e32 v22, v21, v20
	v_fma_f32 v23, -v19, v22, v21
	v_fmac_f32_e32 v22, v23, v20
	v_fma_f32 v19, -v19, v22, v21
	v_div_fmas_f32 v19, v19, v20, v22
	global_load_dwordx4 v[20:23], v[68:69], off
	global_load_dwordx4 v[186:189], v[68:69], off offset:1024
	global_load_dwordx4 v[190:193], v[68:69], off offset:2048
	global_load_dwordx4 v[194:197], v[68:69], off offset:3072
	v_div_fixup_f32 v18, v19, v18, 1.0
	v_pk_mul_f32 v[10:11], v[12:13], v[18:19] op_sel_hi:[1,0]
	v_pk_mul_f32 v[24:25], v[24:25], v[18:19] op_sel_hi:[1,0]
	s_waitcnt vmcnt(0)
	v_mov_b32_e32 v27, v22
	v_mov_b32_e32 v22, v21
	v_mov_b32_e32 v26, v20
	v_pk_mul_f32 v[10:11], v[22:23], v[10:11]
	v_pk_mul_f32 v[24:25], v[26:27], v[24:25]
	v_and_b32_sdwa v19, v11, v200 dst_sel:DWORD dst_unused:UNUSED_PAD src0_sel:WORD_1 src1_sel:DWORD
	v_and_b32_sdwa v12, v25, v200 dst_sel:DWORD dst_unused:UNUSED_PAD src0_sel:WORD_1 src1_sel:DWORD
	v_and_b32_sdwa v20, v10, v200 dst_sel:DWORD dst_unused:UNUSED_PAD src0_sel:WORD_1 src1_sel:DWORD
	v_add3_u32 v11, v11, v19, s34
	v_and_b32_sdwa v13, v24, v200 dst_sel:DWORD dst_unused:UNUSED_PAD src0_sel:WORD_1 src1_sel:DWORD
	v_add3_u32 v12, v25, v12, s34
	v_add3_u32 v10, v10, v20, s34
	v_and_b32_e32 v11, 0xffff0000, v11
	v_add3_u32 v13, v24, v13, s34
	v_and_b32_e32 v10, 0xffff0000, v10
	v_or_b32_sdwa v11, v11, v12 dst_sel:DWORD dst_unused:UNUSED_PAD src0_sel:DWORD src1_sel:WORD_1
	v_add_co_u32_e32 v12, vcc, s88, v72
	v_or_b32_sdwa v10, v10, v13 dst_sel:DWORD dst_unused:UNUSED_PAD src0_sel:DWORD src1_sel:WORD_1
	s_nop 0
	v_addc_co_u32_e32 v13, vcc, -1, v73, vcc
	global_store_dwordx2 v[12:13], v[10:11], off
	s_nop 1
	v_mov_b32_e32 v10, v186
	v_mov_b32_e32 v11, v187
	v_mov_b32_e32 v12, v188
	v_mov_b32_e32 v13, v189
	v_mov_b32_e32 v21, v16
	v_mov_b32_e32 v16, v15
	v_mov_b32_e32 v20, v14
	v_pk_mul_f32 v[14:15], v[16:17], v[18:19] op_sel_hi:[1,0]
	v_pk_mul_f32 v[20:21], v[20:21], v[18:19] op_sel_hi:[1,0]
	v_mov_b32_e32 v17, v6
	v_mov_b32_e32 v6, v5
	v_mov_b32_e32 v16, v4
	v_pk_mul_f32 v[4:5], v[6:7], v[18:19] op_sel_hi:[1,0]
	v_pk_mul_f32 v[16:17], v[16:17], v[18:19] op_sel_hi:[1,0]
	v_mov_b32_e32 v23, v12
	v_mov_b32_e32 v12, v11
	v_mov_b32_e32 v22, v10
	v_pk_mul_f32 v[10:11], v[12:13], v[14:15]
	v_pk_mul_f32 v[20:21], v[22:23], v[20:21]
	v_and_b32_sdwa v14, v11, v200 dst_sel:DWORD dst_unused:UNUSED_PAD src0_sel:WORD_1 src1_sel:DWORD
	v_and_b32_sdwa v15, v10, v200 dst_sel:DWORD dst_unused:UNUSED_PAD src0_sel:WORD_1 src1_sel:DWORD
	v_and_b32_sdwa v12, v21, v200 dst_sel:DWORD dst_unused:UNUSED_PAD src0_sel:WORD_1 src1_sel:DWORD
	v_and_b32_sdwa v13, v20, v200 dst_sel:DWORD dst_unused:UNUSED_PAD src0_sel:WORD_1 src1_sel:DWORD
	v_add3_u32 v11, v11, v14, s34
	v_add3_u32 v10, v10, v15, s34
	v_add3_u32 v13, v20, v13, s34
	v_add3_u32 v12, v21, v12, s34
	v_and_b32_e32 v11, 0xffff0000, v11
	v_and_b32_e32 v10, 0xffff0000, v10
	v_add_co_u32_e32 v14, vcc, s3, v72
	v_or_b32_sdwa v11, v11, v12 dst_sel:DWORD dst_unused:UNUSED_PAD src0_sel:DWORD src1_sel:WORD_1
	v_or_b32_sdwa v10, v10, v13 dst_sel:DWORD dst_unused:UNUSED_PAD src0_sel:DWORD src1_sel:WORD_1
	v_addc_co_u32_e32 v15, vcc, -1, v73, vcc
	global_store_dwordx2 v[14:15], v[10:11], off offset:-3584
	s_nop 1
	v_mov_b32_e32 v10, v190
	v_mov_b32_e32 v11, v191
	v_mov_b32_e32 v12, v192
	v_mov_b32_e32 v13, v193
	v_mov_b32_e32 v21, v12
	v_mov_b32_e32 v12, v11
	v_mov_b32_e32 v20, v10
	v_pk_mul_f32 v[4:5], v[12:13], v[4:5]
	v_pk_mul_f32 v[16:17], v[20:21], v[16:17]
	v_and_b32_sdwa v10, v5, v200 dst_sel:DWORD dst_unused:UNUSED_PAD src0_sel:WORD_1 src1_sel:DWORD
	v_and_b32_sdwa v11, v4, v200 dst_sel:DWORD dst_unused:UNUSED_PAD src0_sel:WORD_1 src1_sel:DWORD
	v_and_b32_sdwa v6, v17, v200 dst_sel:DWORD dst_unused:UNUSED_PAD src0_sel:WORD_1 src1_sel:DWORD
	v_and_b32_sdwa v7, v16, v200 dst_sel:DWORD dst_unused:UNUSED_PAD src0_sel:WORD_1 src1_sel:DWORD
	v_add3_u32 v5, v5, v10, s34
	v_add3_u32 v4, v4, v11, s34
	v_add3_u32 v7, v16, v7, s34
	v_add3_u32 v6, v17, v6, s34
	v_and_b32_e32 v5, 0xffff0000, v5
	v_and_b32_e32 v4, 0xffff0000, v4
	v_or_b32_sdwa v5, v5, v6 dst_sel:DWORD dst_unused:UNUSED_PAD src0_sel:DWORD src1_sel:WORD_1
	v_or_b32_sdwa v4, v4, v7 dst_sel:DWORD dst_unused:UNUSED_PAD src0_sel:DWORD src1_sel:WORD_1
	global_store_dwordx2 v[14:15], v[4:5], off offset:-3072
	s_nop 1
	v_mov_b32_e32 v4, v194
	v_mov_b32_e32 v5, v195
	v_mov_b32_e32 v6, v196
	v_mov_b32_e32 v7, v197
	v_mov_b32_e32 v11, v2
	v_mov_b32_e32 v2, v1
	v_mov_b32_e32 v10, v0
	v_pk_mul_f32 v[0:1], v[2:3], v[18:19] op_sel_hi:[1,0]
	v_pk_mul_f32 v[10:11], v[10:11], v[18:19] op_sel_hi:[1,0]
	v_mov_b32_e32 v13, v6
	v_mov_b32_e32 v6, v5
	v_mov_b32_e32 v12, v4
	v_pk_mul_f32 v[0:1], v[0:1], v[6:7]
	v_pk_mul_f32 v[10:11], v[10:11], v[12:13]
	v_and_b32_sdwa v4, v1, v200 dst_sel:DWORD dst_unused:UNUSED_PAD src0_sel:WORD_1 src1_sel:DWORD
	v_and_b32_sdwa v5, v0, v200 dst_sel:DWORD dst_unused:UNUSED_PAD src0_sel:WORD_1 src1_sel:DWORD
	v_and_b32_sdwa v2, v11, v200 dst_sel:DWORD dst_unused:UNUSED_PAD src0_sel:WORD_1 src1_sel:DWORD
	v_and_b32_sdwa v3, v10, v200 dst_sel:DWORD dst_unused:UNUSED_PAD src0_sel:WORD_1 src1_sel:DWORD
	v_add3_u32 v1, v1, v4, s34
	v_add3_u32 v0, v0, v5, s34
	v_add3_u32 v3, v10, v3, s34
	v_add3_u32 v2, v11, v2, s34
	v_and_b32_e32 v1, 0xffff0000, v1
	v_and_b32_e32 v0, 0xffff0000, v0
	v_or_b32_sdwa v1, v1, v2 dst_sel:DWORD dst_unused:UNUSED_PAD src0_sel:DWORD src1_sel:WORD_1
	v_or_b32_sdwa v0, v0, v3 dst_sel:DWORD dst_unused:UNUSED_PAD src0_sel:DWORD src1_sel:WORD_1
	global_store_dwordx2 v[14:15], v[0:1], off offset:-2560
	s_branch .LBB0_120
